# h9 + last DA tile runs inside the optimized main loop (loop bound +1 tile, peeled copy skipped)
# baseline (speedup 1.0000x reference)
; #define LAS __attribute__((address_space(3)))
; template <int MODE> ...
;     ...
;     for (int kt = kt_lo; kt <= kt_hi; ++kt) {
;         const int bufsel = (kt - kt_lo) & 1;
;     ...
;         if (more) {
;             LAS unsigned char* kb = lds + (bufsel ^ 1) * AT_BUF; LAS unsigned char* vb = kb + AT_KBYTES;
;             *(LAS u32x4*)(kb + kp_row0 * AT_KROW + kp_c * 16) = kr0; *(LAS u32x4*)(kb + (kp_row0 + 32) * AT_KROW + kp_c * 16) = kr1;
;             { LAS unsigned char* p0 = vb + vp_row0 * AT_VROW + vp_c * 16; LAS unsigned char* p1 = vb + (vp_row0 + 64) * AT_VROW + vp_c * 16;
;           *(LAS u32x2*)p0 = (u32x2){vr0.x, vr0.y}; *(LAS u32x2*)(p0 + 8) = (u32x2){vr0.z, vr0.w}; *(LAS u32x2*)p1 = (u32x2){vr1.x, vr1.y}; *(LAS u32x2*)(p1 + 8) = (u32x2){vr1.z, vr1.w}; }
;         }
.LBB0_387:
	s_xor_b32 s14, s29, 1
	s_mul_i32 s14, s14, 0x8800
	s_add_i32 s14, s14, 0
	v_add3_u32 v0, s14, v137, v138
	s_waitcnt vmcnt(3)
	ds_write_b128 v0, v[2:5]
	v_add3_u32 v0, s14, v195, v138
	s_waitcnt vmcnt(2)
	ds_write_b128 v0, v[6:9]
	v_add3_u32 v0, s14, v196, v140
	s_add_i32 s25, s25, 1
	v_add_u32_e32 v2, 0x4400, v0
	v_lshl_add_u64 v[142:143], v[142:143], 0, s[96:97]
	v_subrev_u32_e32 v199, 64, v199
	v_add_u32_e32 v200, 0xffffff00, v200
	s_sub_i32 s14, s28, 64
	s_cmp_eq_u32 s33, s14
	v_lshl_add_u64 v[144:145], v[144:145], 0, s[94:95]
	v_add_u32_e32 v0, 0x6600, v0
	s_waitcnt vmcnt(1)
	ds_write2_b64 v2, v[10:11], v[12:13] offset1:1
	s_waitcnt vmcnt(0)
	ds_write2_b64 v0, v[128:129], v[130:131] offset1:1
	s_cbranch_scc1 .LBB0_389
	s_mov_b32 s14, s28
	s_branch .LBB0_381

; #define LAS __attribute__((address_space(3)))
; template <int MODE> ...
;     ...
;     for (int kt = kt_lo; kt <= kt_hi; ++kt) {
;         const int bufsel = (kt - kt_lo) & 1;
;     ...
;         if (more) {
;             LAS unsigned char* kb = lds + (bufsel ^ 1) * AT_BUF; LAS unsigned char* vb = kb + AT_KBYTES;
;             *(LAS u32x4*)(kb + kp_row0 * AT_KROW + kp_c * 16) = kr0; *(LAS u32x4*)(kb + (kp_row0 + 32) * AT_KROW + kp_c * 16) = kr1;
;             { LAS unsigned char* p0 = vb + vp_row0 * AT_VROW + vp_c * 16; LAS unsigned char* p1 = vb + (vp_row0 + 64) * AT_VROW + vp_c * 16;
;           *(LAS u32x2*)p0 = (u32x2){vr0.x, vr0.y}; *(LAS u32x2*)(p0 + 8) = (u32x2){vr0.z, vr0.w}; *(LAS u32x2*)p1 = (u32x2){vr1.x, vr1.y}; *(LAS u32x2*)(p1 + 8) = (u32x2){vr1.z, vr1.w}; }
;         }
.LBB0_408:
	s_xor_b32 s0, s9, 1
	s_mul_i32 s0, s0, 0x8800
	s_add_i32 s0, s0, 0
	v_add3_u32 v0, s0, v198, v136
	s_waitcnt vmcnt(3)
	ds_write_b128 v0, v[2:5]
	v_add3_u32 v0, s0, v200, v136
	s_waitcnt vmcnt(2)
	ds_write_b128 v0, v[6:9]
	v_add3_u32 v0, s0, v199, v138
	s_add_i32 s19, s19, 1
	v_add_u32_e32 v2, 0x4400, v0
	v_lshl_add_u64 v[142:143], v[142:143], 0, s[96:97]
	v_subrev_u32_e32 v201, 64, v201
	v_add_u32_e32 v202, 0xffffff00, v202
	s_sub_i32 s0, s8, 64
	s_cmp_eq_u32 s89, s0
	v_lshl_add_u64 v[144:145], v[144:145], 0, s[94:95]
	v_add_u32_e32 v0, 0x6600, v0
	s_waitcnt vmcnt(1)
	ds_write2_b64 v2, v[10:11], v[12:13] offset1:1
	s_waitcnt vmcnt(0)
	ds_write2_b64 v0, v[128:129], v[130:131] offset1:1
	s_cbranch_scc1 .LBB0_410
	s_mov_b32 s0, s8
	s_branch .LBB0_402
